# RWKV prefetch loads bf16 straight into the high halves of the staging input registers (global_load_short_d16_hi): the 35 shift conversions per wave and block are gone
# speedup vs baseline: 1.0071x; 1.0071x over previous
.LBB0_564:
	v_mov_b32_e32 v78, v75
	v_mov_b32_e32 v76, v77
	s_and_b32 s3, s40, 1
	v_add_u32_e32 v28, s72, v76
	v_ashrrev_i32_e32 v29, 31, v28
	v_lshlrev_b64 v[10:11], 2, v[28:29]
	s_and_b32 s3, s40, 1
	s_mov_b32 s0, 0x17800
	s_mov_b32 s1, 0x1b800
	s_cmp_eq_u32 s3, 0
	s_cselect_b32 s41, 0x11800, s0
	s_cselect_b32 s16, 0x23800, s1
	v_lshlrev_b32_e32 v26, 3, v78
	v_mul_u32_u24_e32 v166, 0x880, v78
	v_lshl_add_u32 v166, v76, 2, v166
	v_lshlrev_b32_e32 v167, 11, v78
	v_lshl_add_u32 v167, v76, 2, v167
	v_add_u32_e32 v167, s41, v167
	v_mov_b32_e32 v140, 1.0
	v_sub_f32_e32 v169, v106, v44
	v_sub_f32_e32 v170, v35, v46
	v_sub_f32_e32 v171, v34, v48
	v_fma_f32 v169, v169, v115, v44
	v_fma_f32 v170, v170, v116, v46
	v_fma_f32 v171, v171, v119, v48
	v_add_f32_e32 v172, v50, v117
	v_add_f32_e32 v173, v107, v118
	v_mul_f32_e32 v172, 0xbfb8aa3b, v172
	v_mul_f32_e32 v173, 0xbfb8aa3b, v173
	v_exp_f32_e32 v172, v172
	v_exp_f32_e32 v173, v173
	ds_write_b32 v167, v171 offset:0
	v_add_f32_e32 v172, 1.0, v172
	v_add_f32_e32 v173, 1.0, v173
	v_rcp_f32_e32 v172, v172
	v_rcp_f32_e32 v173, v173
	v_mul_f32_e32 v124, v170, v120
	v_mul_f32_e32 v173, 0xbf1b4598, v173
	v_add_f32_e32 v174, -1.0, v172
	v_mul_f32_e32 v173, 0x3fb8aa3b, v173
	v_fma_f32 v174, v121, v174, 1.0
	v_exp_f32_e32 v173, v173
	v_mul_f32_e32 v174, v170, v174
	v_mul_f32_e32 v150, v124, v124
	v_mul_f32_e32 v175, v169, v174
	v_mul_f32_e32 v141, v140, v173
	v_mul_f32_e32 v158, v122, v175
	v_rcp_f32_e32 v176, v141
	v_mul_f32_e32 v169, v169, v141
	v_mul_f32_e32 v174, v174, v176
	v_mul_f32_e32 v132, v172, v176
	ds_write_b32 v166, v169 offset:17408
	ds_write_b32 v166, v174 offset:52224
	v_sub_f32_e32 v169, v44, v1
	v_sub_f32_e32 v170, v46, v45
	v_sub_f32_e32 v171, v48, v47
	v_fma_f32 v169, v169, v115, v1
	v_fma_f32 v170, v170, v116, v45
	v_fma_f32 v171, v171, v119, v47
	v_add_f32_e32 v172, v51, v117
	v_add_f32_e32 v173, v108, v118
	v_mul_f32_e32 v172, 0xbfb8aa3b, v172
	v_mul_f32_e32 v173, 0xbfb8aa3b, v173
	v_exp_f32_e32 v172, v172
	v_exp_f32_e32 v173, v173
	ds_write_b32 v167, v171 offset:256
	v_add_f32_e32 v172, 1.0, v172
	v_add_f32_e32 v173, 1.0, v173
	v_rcp_f32_e32 v172, v172
	v_rcp_f32_e32 v173, v173
	v_mul_f32_e32 v125, v170, v120
	v_mul_f32_e32 v173, 0xbf1b4598, v173
	v_add_f32_e32 v174, -1.0, v172
	v_mul_f32_e32 v173, 0x3fb8aa3b, v173
	v_fma_f32 v174, v121, v174, 1.0
	v_exp_f32_e32 v173, v173
	v_mul_f32_e32 v174, v170, v174
	v_mul_f32_e32 v152, v125, v125
	v_mul_f32_e32 v175, v169, v174
	v_mul_f32_e32 v142, v141, v173
	v_mul_f32_e32 v160, v122, v175
	v_rcp_f32_e32 v176, v142
	v_mul_f32_e32 v169, v169, v142
	v_mul_f32_e32 v174, v174, v176
	v_mul_f32_e32 v133, v172, v176
	ds_write_b32 v166, v169 offset:17680
	ds_write_b32 v166, v174 offset:52496
	v_sub_f32_e32 v169, v1, v52
	v_sub_f32_e32 v170, v45, v54
	v_sub_f32_e32 v171, v47, v56
	v_fma_f32 v169, v169, v115, v52
	v_fma_f32 v170, v170, v116, v54
	v_fma_f32 v171, v171, v119, v56
	v_add_f32_e32 v172, v58, v117
	v_add_f32_e32 v173, v109, v118
	v_mul_f32_e32 v172, 0xbfb8aa3b, v172
	v_mul_f32_e32 v173, 0xbfb8aa3b, v173
	v_exp_f32_e32 v172, v172
	v_exp_f32_e32 v173, v173
	ds_write_b32 v167, v171 offset:512
	v_add_f32_e32 v172, 1.0, v172
	v_add_f32_e32 v173, 1.0, v173
	v_rcp_f32_e32 v172, v172
	v_rcp_f32_e32 v173, v173
	v_mul_f32_e32 v126, v170, v120
	v_mul_f32_e32 v173, 0xbf1b4598, v173
	v_add_f32_e32 v174, -1.0, v172
	v_mul_f32_e32 v173, 0x3fb8aa3b, v173
	v_fma_f32 v174, v121, v174, 1.0
	v_exp_f32_e32 v173, v173
	v_mul_f32_e32 v174, v170, v174
	v_mul_f32_e32 v151, v126, v126
	v_mul_f32_e32 v175, v169, v174
	v_mul_f32_e32 v143, v142, v173
	v_mul_f32_e32 v159, v122, v175
	v_rcp_f32_e32 v176, v143
	v_mul_f32_e32 v169, v169, v143
	v_mul_f32_e32 v174, v174, v176
	v_mul_f32_e32 v134, v172, v176
	ds_write_b32 v166, v169 offset:17952
	ds_write_b32 v166, v174 offset:52768
	v_sub_f32_e32 v169, v52, v49
	v_sub_f32_e32 v170, v54, v53
	v_sub_f32_e32 v171, v56, v55
	v_fma_f32 v169, v169, v115, v49
	v_fma_f32 v170, v170, v116, v53
	v_fma_f32 v171, v171, v119, v55
	v_add_f32_e32 v172, v57, v117
	v_add_f32_e32 v173, v110, v118
	v_mul_f32_e32 v172, 0xbfb8aa3b, v172
	v_mul_f32_e32 v173, 0xbfb8aa3b, v173
	v_exp_f32_e32 v172, v172
	v_exp_f32_e32 v173, v173
	ds_write_b32 v167, v171 offset:768
	v_add_f32_e32 v172, 1.0, v172
	v_add_f32_e32 v173, 1.0, v173
	v_rcp_f32_e32 v172, v172
	v_rcp_f32_e32 v173, v173
	v_mul_f32_e32 v127, v170, v120
	v_mul_f32_e32 v173, 0xbf1b4598, v173
	v_add_f32_e32 v174, -1.0, v172
	v_mul_f32_e32 v173, 0x3fb8aa3b, v173
	v_fma_f32 v174, v121, v174, 1.0
	v_exp_f32_e32 v173, v173
	v_mul_f32_e32 v174, v170, v174
	v_mul_f32_e32 v153, v127, v127
	v_mul_f32_e32 v175, v169, v174
	v_mul_f32_e32 v144, v143, v173
	v_mul_f32_e32 v161, v122, v175
	v_rcp_f32_e32 v176, v144
	v_mul_f32_e32 v169, v169, v144
	v_mul_f32_e32 v174, v174, v176
	v_mul_f32_e32 v135, v172, v176
	ds_write_b32 v166, v169 offset:18224
	ds_write_b32 v166, v174 offset:53040
	v_sub_f32_e32 v169, v49, v60
	v_sub_f32_e32 v170, v53, v62
	v_sub_f32_e32 v171, v55, v64
	v_fma_f32 v169, v169, v115, v60
	v_fma_f32 v170, v170, v116, v62
	v_fma_f32 v171, v171, v119, v64
	v_add_f32_e32 v172, v66, v117
	v_add_f32_e32 v173, v111, v118
	v_mul_f32_e32 v172, 0xbfb8aa3b, v172
	v_mul_f32_e32 v173, 0xbfb8aa3b, v173
	v_exp_f32_e32 v172, v172
	v_exp_f32_e32 v173, v173
	ds_write_b32 v167, v171 offset:1024
	v_add_f32_e32 v172, 1.0, v172
	v_add_f32_e32 v173, 1.0, v173
	v_rcp_f32_e32 v172, v172
	v_rcp_f32_e32 v173, v173
	v_mul_f32_e32 v128, v170, v120
	v_mul_f32_e32 v173, 0xbf1b4598, v173
	v_add_f32_e32 v174, -1.0, v172
	v_mul_f32_e32 v173, 0x3fb8aa3b, v173
	v_fma_f32 v174, v121, v174, 1.0
	v_exp_f32_e32 v173, v173
	v_mul_f32_e32 v174, v170, v174
	v_mul_f32_e32 v154, v128, v128
	v_mul_f32_e32 v175, v169, v174
	v_mul_f32_e32 v145, v144, v173
	v_mul_f32_e32 v162, v122, v175
	v_rcp_f32_e32 v176, v145
	v_mul_f32_e32 v169, v169, v145
	v_mul_f32_e32 v174, v174, v176
	v_mul_f32_e32 v136, v172, v176
	ds_write_b32 v166, v169 offset:18496
	ds_write_b32 v166, v174 offset:53312
	v_sub_f32_e32 v169, v60, v59
	v_sub_f32_e32 v170, v62, v61
	v_sub_f32_e32 v171, v64, v63
	v_fma_f32 v169, v169, v115, v59
	v_fma_f32 v170, v170, v116, v61
	v_fma_f32 v171, v171, v119, v63
	v_add_f32_e32 v172, v65, v117
	v_add_f32_e32 v173, v112, v118
	v_mul_f32_e32 v172, 0xbfb8aa3b, v172
	v_mul_f32_e32 v173, 0xbfb8aa3b, v173
	v_exp_f32_e32 v172, v172
	v_exp_f32_e32 v173, v173
	ds_write_b32 v167, v171 offset:1280
	v_add_f32_e32 v172, 1.0, v172
	v_add_f32_e32 v173, 1.0, v173
	v_rcp_f32_e32 v172, v172
	v_rcp_f32_e32 v173, v173
	v_mul_f32_e32 v129, v170, v120
	v_mul_f32_e32 v173, 0xbf1b4598, v173
	v_add_f32_e32 v174, -1.0, v172
	v_mul_f32_e32 v173, 0x3fb8aa3b, v173
	v_fma_f32 v174, v121, v174, 1.0
	v_exp_f32_e32 v173, v173
	v_mul_f32_e32 v174, v170, v174
	v_mul_f32_e32 v156, v129, v129
	v_mul_f32_e32 v175, v169, v174
	v_mul_f32_e32 v146, v145, v173
	v_mul_f32_e32 v164, v122, v175
	v_rcp_f32_e32 v176, v146
	v_mul_f32_e32 v169, v169, v146
	v_mul_f32_e32 v174, v174, v176
	v_mul_f32_e32 v137, v172, v176
	ds_write_b32 v166, v169 offset:18768
	ds_write_b32 v166, v174 offset:53584
	v_sub_f32_e32 v169, v59, v67
	v_sub_f32_e32 v170, v61, v69
	v_sub_f32_e32 v171, v63, v71
	v_fma_f32 v169, v169, v115, v67
	v_fma_f32 v170, v170, v116, v69
	v_fma_f32 v171, v171, v119, v71
	v_add_f32_e32 v172, v74, v117
	v_add_f32_e32 v173, v113, v118
	v_mul_f32_e32 v172, 0xbfb8aa3b, v172
	v_mul_f32_e32 v173, 0xbfb8aa3b, v173
	v_exp_f32_e32 v172, v172
	v_exp_f32_e32 v173, v173
	ds_write_b32 v167, v171 offset:1536
	v_add_f32_e32 v172, 1.0, v172
	v_add_f32_e32 v173, 1.0, v173
	v_rcp_f32_e32 v172, v172
	v_rcp_f32_e32 v173, v173
	v_mul_f32_e32 v130, v170, v120
	v_mul_f32_e32 v173, 0xbf1b4598, v173
	v_add_f32_e32 v174, -1.0, v172
	v_mul_f32_e32 v173, 0x3fb8aa3b, v173
	v_fma_f32 v174, v121, v174, 1.0
	v_exp_f32_e32 v173, v173
	v_mul_f32_e32 v174, v170, v174
	v_mul_f32_e32 v155, v130, v130
	v_mul_f32_e32 v175, v169, v174
	v_mul_f32_e32 v147, v146, v173
	v_mul_f32_e32 v163, v122, v175
	v_rcp_f32_e32 v176, v147
	v_mul_f32_e32 v169, v169, v147
	v_mul_f32_e32 v174, v174, v176
	v_mul_f32_e32 v138, v172, v176
	ds_write_b32 v166, v169 offset:19040
	ds_write_b32 v166, v174 offset:53856
	v_sub_f32_e32 v169, v67, v68
	v_sub_f32_e32 v170, v69, v70
	v_sub_f32_e32 v171, v71, v72
	v_fma_f32 v169, v169, v115, v68
	v_fma_f32 v170, v170, v116, v70
	v_fma_f32 v171, v171, v119, v72
	v_add_f32_e32 v172, v73, v117
	v_add_f32_e32 v173, v114, v118
	v_mul_f32_e32 v172, 0xbfb8aa3b, v172
	v_mul_f32_e32 v173, 0xbfb8aa3b, v173
	v_exp_f32_e32 v172, v172
	v_exp_f32_e32 v173, v173
	ds_write_b32 v167, v171 offset:1792
	v_add_f32_e32 v172, 1.0, v172
	v_add_f32_e32 v173, 1.0, v173
	v_rcp_f32_e32 v172, v172
	v_rcp_f32_e32 v173, v173
	v_mul_f32_e32 v131, v170, v120
	v_mul_f32_e32 v173, 0xbf1b4598, v173
	v_add_f32_e32 v174, -1.0, v172
	v_mul_f32_e32 v173, 0x3fb8aa3b, v173
	v_fma_f32 v174, v121, v174, 1.0
	v_exp_f32_e32 v173, v173
	v_mul_f32_e32 v174, v170, v174
	v_mul_f32_e32 v157, v131, v131
	v_mul_f32_e32 v175, v169, v174
	v_mul_f32_e32 v148, v147, v173
	v_mul_f32_e32 v165, v122, v175
	v_rcp_f32_e32 v176, v148
	v_mul_f32_e32 v169, v169, v148
	v_mul_f32_e32 v174, v174, v176
	v_mul_f32_e32 v139, v172, v176
	ds_write_b32 v166, v169 offset:19312
	ds_write_b32 v166, v174 offset:54128
	v_permlane32_swap_b32_e32 v150, v151
	v_permlane32_swap_b32_e32 v152, v153
	v_permlane32_swap_b32_e32 v154, v155
	v_permlane32_swap_b32_e32 v156, v157
	v_permlane32_swap_b32_e32 v158, v159
	v_permlane32_swap_b32_e32 v160, v161
	v_permlane32_swap_b32_e32 v162, v163
	v_permlane32_swap_b32_e32 v164, v165
	v_add_f32_e32 v182, v150, v151
	v_add_f32_e32 v183, v152, v153
	v_add_f32_e32 v184, v154, v155
	v_add_f32_e32 v185, v156, v157
	v_add_f32_e32 v186, v158, v159
	v_add_f32_e32 v187, v160, v161
	v_add_f32_e32 v188, v162, v163
	v_add_f32_e32 v189, v164, v165
	v_permlane16_swap_b32_e32 v182, v183
	v_permlane16_swap_b32_e32 v184, v185
	v_permlane16_swap_b32_e32 v186, v187
	v_permlane16_swap_b32_e32 v188, v189
	v_add_f32_e32 v190, v182, v183
	v_add_f32_e32 v191, v184, v185
	v_add_f32_e32 v192, v186, v187
	v_add_f32_e32 v193, v188, v189
	v_add_f32_dpp v194, v190, v190 row_mirror row_mask:0xf bank_mask:0x3
	v_add_f32_dpp v194, v191, v191 row_mirror row_mask:0xf bank_mask:0xc
	v_add_f32_dpp v195, v192, v192 row_mirror row_mask:0xf bank_mask:0x3
	v_add_f32_dpp v195, v193, v193 row_mirror row_mask:0xf bank_mask:0xc
	v_add_f32_dpp v196, v194, v194 row_half_mirror row_mask:0xf bank_mask:0x5
	s_nop 0
	v_add_f32_dpp v196, v195, v195 row_half_mirror row_mask:0xf bank_mask:0xa
	s_nop 1
	v_add_f32_dpp v196, v196, v196 quad_perm:[1,0,3,2] row_mask:0xf bank_mask:0xf
	s_nop 1
	v_add_f32_dpp v196, v196, v196 quad_perm:[2,3,0,1] row_mask:0xf bank_mask:0xf
	v_add_f32_e32 v197, 0x2b8cbccc, v196
	v_lshrrev_b32_e32 v198, 4, v76
	v_rsq_f32_e32 v197, v197
	v_bfe_u32 v168, v76, 3, 1
	v_lshl_add_u32 v198, v168, 2, v198
	v_add_u32_e32 v198, v198, v26
	v_lshl_add_u32 v198, v198, 2, s16
	s_mov_b32 s4, 0x10101010
	s_mov_b32 s5, 0x10101010
	s_mov_b64 exec, s[4:5]
	ds_write_b32 v198, v196
	s_mov_b64 exec, -1
	v_readlane_b32 s0, v197, 0
	v_readlane_b32 s1, v197, 16
	v_readlane_b32 s3, v197, 32
	v_readlane_b32 s4, v197, 48
	v_mul_f32_e32 v124, s0, v124
	v_mul_f32_e32 v125, s1, v125
	v_mul_f32_e32 v126, s3, v126
	v_mul_f32_e32 v127, s4, v127
	v_mul_f32_e64 v169, v124, -v140
	v_mul_f32_e32 v132, v124, v132
	v_mul_f32_e64 v170, v125, -v141
	v_mul_f32_e32 v133, v125, v133
	v_mul_f32_e64 v171, v126, -v142
	v_mul_f32_e32 v134, v126, v134
	v_mul_f32_e64 v172, v127, -v143
	v_mul_f32_e32 v135, v127, v135
	ds_write_b32 v166, v169 offset:0
	ds_write_b32 v166, v132 offset:34816
	ds_write_b32 v166, v170 offset:272
	ds_write_b32 v166, v133 offset:35088
	ds_write_b32 v166, v171 offset:544
	ds_write_b32 v166, v134 offset:35360
	ds_write_b32 v166, v172 offset:816
	ds_write_b32 v166, v135 offset:35632
	v_readlane_b32 s0, v197, 8
	v_readlane_b32 s1, v197, 24
	v_readlane_b32 s3, v197, 40
	v_readlane_b32 s4, v197, 56
	v_mul_f32_e32 v128, s0, v128
	v_mul_f32_e32 v129, s1, v129
	v_mul_f32_e32 v130, s3, v130
	v_mul_f32_e32 v131, s4, v131
	v_mul_f32_e64 v169, v128, -v144
	v_mul_f32_e32 v136, v128, v136
	v_mul_f32_e64 v170, v129, -v145
	v_mul_f32_e32 v137, v129, v137
	v_mul_f32_e64 v171, v130, -v146
	v_mul_f32_e32 v138, v130, v138
	v_mul_f32_e64 v172, v131, -v147
	v_mul_f32_e32 v139, v131, v139
	ds_write_b32 v166, v169 offset:1088
	ds_write_b32 v166, v136 offset:35904
	ds_write_b32 v166, v170 offset:1360
	ds_write_b32 v166, v137 offset:36176
	ds_write_b32 v166, v171 offset:1632
	ds_write_b32 v166, v138 offset:36448
	ds_write_b32 v166, v172 offset:1904
	ds_write_b32 v166, v139 offset:36720
	v_lshlrev_b32_e32 v168, 8, v78
	v_lshl_add_u32 v168, v76, 2, v168
	v_add_u32_e32 v168, 0x11000, v168
	ds_write_b32 v168, v148
	ds_read_b128 v[136:139], v79 offset:0
	ds_read_b128 v[152:155], v79 offset:34816
	ds_read_b128 v[140:143], v79 offset:64
	ds_read_b128 v[156:159], v79 offset:34880
	ds_read_b128 v[144:147], v79 offset:128
	ds_read_b128 v[160:163], v79 offset:34944
	ds_read_b128 v[148:151], v79 offset:192
	ds_read_b128 v[164:167], v79 offset:35008
	v_cmp_ge_u32_e64 s[0:1], 1, v87
	v_cmp_ge_u32_e64 s[4:5], 2, v87
	v_cmp_ge_u32_e64 s[6:7], 3, v87
	v_cmp_ge_u32_e32 vcc, 0, v87
	s_waitcnt lgkmcnt(0)
	v_mfma_f32_16x16x4_f32 v[36:39], v136, v152, 0
	v_mfma_f32_16x16x4_f32 v[40:43], v137, v153, 0
	v_mfma_f32_16x16x4_f32 v[36:39], v138, v154, v[36:39]
	v_mfma_f32_16x16x4_f32 v[40:43], v139, v155, v[40:43]
	v_mfma_f32_16x16x4_f32 v[36:39], v140, v156, v[36:39]
	v_mfma_f32_16x16x4_f32 v[40:43], v141, v157, v[40:43]
	v_mfma_f32_16x16x4_f32 v[36:39], v142, v158, v[36:39]
	v_mfma_f32_16x16x4_f32 v[40:43], v143, v159, v[40:43]
	v_mfma_f32_16x16x4_f32 v[36:39], v144, v160, v[36:39]
	v_mfma_f32_16x16x4_f32 v[40:43], v145, v161, v[40:43]
	v_mfma_f32_16x16x4_f32 v[36:39], v146, v162, v[36:39]
	v_mfma_f32_16x16x4_f32 v[40:43], v147, v163, v[40:43]
	v_mfma_f32_16x16x4_f32 v[36:39], v148, v164, v[36:39]
	v_mfma_f32_16x16x4_f32 v[40:43], v149, v165, v[40:43]
	v_mfma_f32_16x16x4_f32 v[36:39], v150, v166, v[36:39]
	v_mfma_f32_16x16x4_f32 v[40:43], v151, v167, v[40:43]
	s_nop 7
	s_nop 2
	v_pk_add_f32 v[36:37], v[36:37], v[40:41]
	v_pk_add_f32 v[38:39], v[38:39], v[42:43]
	v_cndmask_b32_e32 v36, 0, v36, vcc
	v_cndmask_b32_e64 v37, 0, v37, s[0:1]
	v_cndmask_b32_e64 v38, 0, v38, s[4:5]
	v_cndmask_b32_e64 v39, 0, v39, s[6:7]
	ds_write_b32 v86, v36 offset:0
	ds_write_b32 v86, v37 offset:32
	ds_write_b32 v86, v38 offset:64
	ds_write_b32 v86, v39 offset:96
	ds_read_b128 v[124:127], v92 offset:32
	ds_read_b128 v[128:131], v92 offset:64
	ds_read_b128 v[132:135], v92 offset:96
	ds_read_b128 v[136:139], v92 offset:128
	ds_read_b128 v[144:147], v92 offset:160
	ds_read_b128 v[148:151], v92 offset:176
	ds_read_b128 v[152:155], v92 offset:192
	ds_read_b128 v[156:159], v92 offset:208
	ds_read_b128 v[160:163], v92 offset:224
	ds_read_b128 v[164:167], v92 offset:240
	ds_read_b128 v[182:185], v93 offset:512
	ds_read_b128 v[186:189], v93 offset:528
	ds_read_b128 v[190:193], v93 offset:544
	ds_read_b128 v[194:197], v93 offset:560
	v_cmp_eq_u32_e32 vcc, 0, v102
	v_cndmask_b32_e32 v36, 0, v103, vcc
	v_cmp_eq_u32_e32 vcc, 1, v102
	v_cndmask_b32_e32 v37, 0, v103, vcc
	v_cmp_eq_u32_e32 vcc, 2, v102
	v_cndmask_b32_e32 v38, 0, v103, vcc
	v_cmp_eq_u32_e32 vcc, 3, v102
	v_cndmask_b32_e32 v39, 0, v103, vcc
	v_cmp_eq_u32_e32 vcc, 4, v102
	v_cndmask_b32_e32 v40, 0, v103, vcc
	v_cmp_eq_u32_e32 vcc, 5, v102
	v_cndmask_b32_e32 v41, 0, v103, vcc
	v_cmp_eq_u32_e32 vcc, 6, v102
	v_cndmask_b32_e32 v42, 0, v103, vcc
	v_cmp_eq_u32_e32 vcc, 7, v102
	v_cndmask_b32_e32 v43, 0, v103, vcc
	s_waitcnt lgkmcnt(0)
	v_fmac_f32_e32 v37, v124, v36
	v_fmac_f32_e32 v38, v128, v36
	v_fmac_f32_e32 v39, v132, v36
	v_fmac_f32_e32 v40, v136, v36
	v_fmac_f32_e32 v41, v144, v36
	v_fmac_f32_e32 v42, v152, v36
	v_fmac_f32_e32 v43, v160, v36
	v_fmac_f32_e32 v38, v129, v37
	v_fmac_f32_e32 v39, v133, v37
	v_fmac_f32_e32 v40, v137, v37
	v_fmac_f32_e32 v41, v145, v37
	v_fmac_f32_e32 v42, v153, v37
	v_fmac_f32_e32 v43, v161, v37
	v_fmac_f32_e32 v39, v134, v38
	v_fmac_f32_e32 v40, v138, v38
	v_fmac_f32_e32 v41, v146, v38
	v_fmac_f32_e32 v42, v154, v38
	v_fmac_f32_e32 v43, v162, v38
	v_fmac_f32_e32 v40, v139, v39
	v_fmac_f32_e32 v41, v147, v39
	v_fmac_f32_e32 v42, v155, v39
	v_fmac_f32_e32 v43, v163, v39
	v_fmac_f32_e32 v41, v148, v40
	v_fmac_f32_e32 v42, v156, v40
	v_fmac_f32_e32 v43, v164, v40
	v_fmac_f32_e32 v42, v157, v41
	v_fmac_f32_e32 v43, v165, v41
	v_fmac_f32_e32 v43, v166, v42
	v_mul_f32_e32 v198, v182, v36
	v_fmac_f32_e32 v198, v183, v37
	v_fmac_f32_e32 v198, v184, v38
	v_fmac_f32_e32 v198, v185, v39
	v_fmac_f32_e32 v198, v186, v40
	v_fmac_f32_e32 v198, v187, v41
	v_fmac_f32_e32 v198, v188, v42
	v_fmac_f32_e32 v198, v189, v43
	v_mul_f32_e32 v199, v190, v36
	v_fmac_f32_e32 v199, v191, v37
	v_fmac_f32_e32 v199, v192, v38
	v_fmac_f32_e32 v199, v193, v39
	v_fmac_f32_e32 v199, v194, v40
	v_fmac_f32_e32 v199, v195, v41
	v_fmac_f32_e32 v199, v196, v42
	v_fmac_f32_e32 v199, v197, v43
	ds_write_b32 v100, v36 offset:0
	ds_write_b32 v100, v37 offset:32
	ds_write_b32 v100, v38 offset:64
	ds_write_b32 v100, v39 offset:96
	ds_write_b32 v100, v40 offset:128
	ds_write_b32 v100, v41 offset:160
	ds_write_b32 v100, v42 offset:192
	ds_write_b32 v100, v43 offset:224
	ds_write_b32 v101, v198 offset:512
	ds_write_b32 v101, v199 offset:544
	s_lshl_b32 s17, s40, 6
	s_cmp_lg_u32 s40, 31
	s_waitcnt lgkmcnt(0)
	s_barrier
	s_cbranch_scc0 .LBB0_586
	v_readfirstlane_b32 s0, v180
	s_nop 1
	s_cmpk_ge_u32 s0, 0x100
	s_cbranch_scc1 .LBB0_586
	s_add_i32 s3, s17, 64
	s_add_u32 s0, s80, s3
	s_addc_u32 s1, s81, 0
	v_ashrrev_i32_e32 v27, 31, v26
	v_lshl_add_u64 v[4:5], s[0:1], 0, v[26:27]
	v_mad_u64_u32 v[2:3], s[0:1], v4, s83, 0
	v_mad_i32_i24 v3, v5, s83, v3
	v_add_u32_e32 v33, s3, v26
	v_mov_b32_e32 v95, v94
	v_lshl_add_u64 v[2:3], s[46:47], 0, v[2:3]
	v_cmp_lt_i32_e32 vcc, 0, v33
	v_mov_b32_e32 v106, 0
	v_lshl_add_u64 v[2:3], v[28:29], 1, v[2:3]
	v_mov_b64_e32 v[34:35], v[94:95]
	s_and_saveexec_b64 s[0:1], vcc
	s_cbranch_execz .LBB0_585
	global_load_short_d16_hi v106, v[2:3], off offset:-3072
	global_load_short_d16_hi v35, v[2:3], off offset:-2048
	global_load_short_d16_hi v34, v[2:3], off offset:-1024
.LBB0_585:
	s_or_b64 exec, exec, s[0:1]
	v_lshlrev_b64 v[4:5], 9, v[4:5]
	v_lshl_add_u64 v[4:5], v[4:5], 0, v[28:29]
	s_mov_b64 s[0:1], 0x200
	v_lshl_add_u64 v[10:11], v[2:3], 0, s[76:77]
	global_load_short_d16_hi v44, v[2:3], off
	global_load_short_d16_hi v1, v[2:3], off offset:3072
	global_load_short_d16_hi v46, v[2:3], off offset:1024
	global_load_short_d16_hi v48, v[2:3], off offset:2048
	v_lshl_add_u64 v[2:3], v[4:5], 0, s[0:1]
	v_lshl_add_u64 v[8:9], v[4:5], 2, s[34:35]
	v_lshl_add_u64 v[12:13], v[2:3], 1, s[62:63]
	v_lshl_add_u64 v[2:3], v[2:3], 2, s[34:35]
	s_mov_b64 s[0:1], 0x400
	v_lshl_add_u64 v[6:7], v[4:5], 1, s[62:63]
	v_lshl_add_u64 v[14:15], v[10:11], 0, s[76:77]
	global_load_dword v107, v[8:9], off
	global_load_short_d16_hi v45, v[10:11], off offset:1024
	global_load_short_d16_hi v47, v[10:11], off offset:2048
	global_load_short_d16_hi v51, v[12:13], off
	global_load_dword v108, v[2:3], off
	global_load_short_d16_hi v54, v[14:15], off offset:1024
	global_load_short_d16_hi v52, v[10:11], off offset:3072
	global_load_short_d16_hi v50, v[6:7], off
	v_lshl_add_u64 v[2:3], v[4:5], 0, s[0:1]
	s_mov_b64 s[0:1], 0x600
	v_lshl_add_u64 v[6:7], v[2:3], 1, s[62:63]
	v_lshl_add_u64 v[2:3], v[2:3], 2, s[34:35]
	v_lshl_add_u64 v[8:9], v[14:15], 0, s[76:77]
	v_lshl_add_u64 v[10:11], v[4:5], 0, s[0:1]
	s_mov_b64 s[0:1], 0x800
	v_lshl_add_u64 v[12:13], v[10:11], 1, s[62:63]
	global_load_dword v109, v[2:3], off
	global_load_short_d16_hi v49, v[14:15], off offset:3072
	global_load_short_d16_hi v53, v[8:9], off offset:1024
	global_load_short_d16_hi v55, v[8:9], off offset:2048
	global_load_short_d16_hi v57, v[12:13], off
	global_load_short_d16_hi v60, v[8:9], off offset:3072
	global_load_short_d16_hi v58, v[6:7], off
	global_load_short_d16_hi v56, v[14:15], off offset:2048
	v_lshl_add_u64 v[6:7], v[8:9], 0, s[76:77]
	v_lshl_add_u64 v[8:9], v[4:5], 0, s[0:1]
	v_lshl_add_u64 v[2:3], v[10:11], 2, s[34:35]
	v_lshl_add_u64 v[10:11], v[8:9], 1, s[62:63]
	v_lshl_add_u64 v[8:9], v[8:9], 2, s[34:35]
	v_lshl_add_u64 v[12:13], v[6:7], 0, s[76:77]
	s_mov_b64 s[0:1], 0xa00
	global_load_dword v110, v[2:3], off
	global_load_dword v111, v[8:9], off
	global_load_short_d16_hi v59, v[6:7], off offset:3072
	global_load_short_d16_hi v61, v[12:13], off offset:1024
	global_load_short_d16_hi v62, v[6:7], off offset:1024
	global_load_short_d16_hi v63, v[12:13], off offset:2048
	global_load_short_d16_hi v66, v[10:11], off
	global_load_short_d16_hi v64, v[6:7], off offset:2048
	v_lshl_add_u64 v[2:3], v[4:5], 0, s[0:1]
	v_lshl_add_u64 v[8:9], v[12:13], 0, s[76:77]
	v_lshl_add_u64 v[6:7], v[2:3], 1, s[62:63]
	v_lshl_add_u64 v[2:3], v[2:3], 2, s[34:35]
	v_lshl_add_u64 v[16:17], v[8:9], 0, s[76:77]
	s_mov_b64 s[0:1], 0xe00
	v_lshl_add_u64 v[10:11], v[4:5], 0, s[76:77]
	global_load_short_d16_hi v65, v[6:7], off
	s_nop 0
	global_load_dword v112, v[2:3], off
	global_load_short_d16_hi v67, v[12:13], off offset:3072
	s_nop 0
	global_load_short_d16_hi v70, v[16:17], off offset:1024
	global_load_short_d16_hi v72, v[16:17], off offset:2048
	s_nop 0
	global_load_short_d16_hi v68, v[8:9], off offset:3072
	global_load_short_d16_hi v69, v[8:9], off offset:1024
	s_nop 0
	global_load_short_d16_hi v71, v[8:9], off offset:2048
	v_lshl_add_u64 v[2:3], v[4:5], 0, s[0:1]
	v_lshl_add_u64 v[14:15], v[10:11], 1, s[62:63]
	v_lshl_add_u64 v[10:11], v[10:11], 2, s[34:35]
	v_lshl_add_u64 v[4:5], v[2:3], 1, s[62:63]
	global_load_dword v113, v[10:11], off
	global_load_short_d16_hi v74, v[14:15], off
	s_nop 0
	global_load_short_d16_hi v73, v[4:5], off
	v_lshl_add_u64 v[2:3], v[2:3], 2, s[34:35]
	global_load_dword v114, v[2:3], off
.LBB0_586:
.Lrw_entry:
	v_readfirstlane_b32 s0, v180
	s_nop 1
	s_cmpk_ge_u32 s0, 0x100
	s_cbranch_scc1 .Lrw_epi
	v_and_b32_e32 v222, 15, v180
	v_bfe_u32 v223, v180, 4, 2
	v_lshrrev_b32_e32 v240, 6, v180
	v_lshrrev_b32_e32 v176, 2, v222
	v_and_b32_e32 v177, 1, v222
	v_lshl_add_u32 v176, v177, 2, v176
	v_lshlrev_b32_e32 v171, 5, v176
	v_mul_u32_u24_e32 v176, 0x110, v176
	v_and_b32_e32 v177, 2, v222
	v_lshl_add_u32 v171, v177, 8, v171
	v_lshl_add_u32 v171, v223, 2, v171
	v_add_u32_e32 v171, 0x15800, v171
	v_mul_u32_u24_e32 v177, 0x2200, v177
	v_lshl_add_u32 v168, v223, 4, v176
	v_add_u32_e32 v168, v168, v177
	v_lshlrev_b32_e32 v178, 6, v240
	v_lshl_add_u32 v178, v222, 2, v178
	v_lshl_add_u32 v178, v223, 8, v178
	v_add_u32_e32 v169, s41, v178
	v_add_u32_e32 v175, 0x1f800, v178
	v_mul_u32_u24_e32 v176, 0x110, v223
	v_lshl_add_u32 v173, v222, 2, v176
	v_add_u32_e32 v173, 0x8800, v173
	v_add_u32_e32 v2, 0x440, v173
	v_add_u32_e32 v3, 0x4400, v173
	v_add_u32_e32 v5, 0x4840, v173
	v_lshlrev_b32_e32 v174, 4, v223
	v_add_u32_e32 v174, 0x11000, v174
	s_mov_b32 s14, 0
	s_mov_b32 s15, 1
	v_mov_b32_e32 v179, 0x27f00
	v_mov_b32_e32 v241, 1
	v_mov_b32_e32 v80, 0
	v_mov_b32_e32 v81, 0
	ds_read_b128 v[128:131], v168 offset:0
	ds_read_b128 v[132:135], v168 offset:64
	ds_read_b128 v[136:139], v168 offset:128
	ds_read_b128 v[140:143], v168 offset:192
	ds_read_b32 v216, v171 offset:256
	ds_read_b32 v217, v171 offset:272
	ds_read_b32 v214, v169 offset:0
	ds_read_b32 v215, v169 offset:1024
	ds_read_b32 v218, v171 offset:0
	ds_read_b32 v219, v171 offset:16
	ds_read2_b32 v[182:183], v173 offset0:0 offset1:16
	ds_read2_b32 v[184:185], v173 offset0:32 offset1:48
	ds_read2_b32 v[186:187], v2 offset0:0 offset1:16
	ds_read2_b32 v[188:189], v2 offset0:32 offset1:48
	ds_read2_b32 v[190:191], v3 offset0:0 offset1:16
	ds_read2_b32 v[192:193], v3 offset0:32 offset1:48
	ds_read2_b32 v[194:195], v5 offset0:0 offset1:16
	ds_read2_b32 v[196:197], v5 offset0:32 offset1:48
	s_mov_b32 s1, 0
	s_waitcnt lgkmcnt(0)
	v_mfma_f32_16x16x4_f32 v[36:39], v128, v224, 0
	v_mfma_f32_16x16x4_f32 v[40:43], v129, v225, 0
	v_mfma_f32_16x16x4_f32 v[36:39], v130, v226, v[36:39]
	v_mfma_f32_16x16x4_f32 v[40:43], v131, v227, v[40:43]
	v_mfma_f32_16x16x4_f32 v[36:39], v132, v228, v[36:39]
	v_mfma_f32_16x16x4_f32 v[40:43], v133, v229, v[40:43]
	v_mfma_f32_16x16x4_f32 v[36:39], v134, v230, v[36:39]
	v_mfma_f32_16x16x4_f32 v[40:43], v135, v231, v[40:43]
	v_mfma_f32_16x16x4_f32 v[36:39], v136, v232, v[36:39]
	v_mfma_f32_16x16x4_f32 v[40:43], v137, v233, v[40:43]
	v_mfma_f32_16x16x4_f32 v[36:39], v138, v234, v[36:39]
	v_mfma_f32_16x16x4_f32 v[40:43], v139, v235, v[40:43]
	v_mfma_f32_16x16x4_f32 v[36:39], v140, v236, v[36:39]
	v_mfma_f32_16x16x4_f32 v[40:43], v141, v237, v[40:43]
	v_mfma_f32_16x16x4_f32 v[36:39], v142, v238, v[36:39]
	v_mfma_f32_16x16x4_f32 v[40:43], v143, v239, v[40:43]
	v_mfma_f32_16x16x4_f32 v[36:39], v216, v214, v[36:39]
	v_mfma_f32_16x16x4_f32 v[40:43], v217, v215, v[40:43]
	v_mfma_f32_16x16x4_f32 v[224:227], v190, v214, v[224:227]
	v_mfma_f32_16x16x4_f32 v[228:231], v191, v214, v[228:231]
	v_mfma_f32_16x16x4_f32 v[232:235], v192, v214, v[232:235]
	v_mfma_f32_16x16x4_f32 v[236:239], v193, v214, v[236:239]
	ds_read_b128 v[128:131], v168 offset:2176
	ds_read_b128 v[132:135], v168 offset:2240
	ds_read_b128 v[136:139], v168 offset:2304
	ds_read_b128 v[140:143], v168 offset:2368
	ds_read_b32 v216, v171 offset:1280
	ds_read_b32 v217, v171 offset:1296
	v_pk_add_f32 v[84:85], v[36:37], v[40:41]
	v_pk_add_f32 v[82:83], v[38:39], v[42:43]
	s_nop 1
	v_mfma_f32_16x16x4_f32 v[88:91], v218, v84, v[80:83]
	v_mfma_f32_16x16x4_f32 v[88:91], v219, v85, v[88:91]
	v_mfma_f32_16x16x4_f32 v[224:227], v194, v215, v[224:227]
	v_mfma_f32_16x16x4_f32 v[228:231], v195, v215, v[228:231]
	v_mfma_f32_16x16x4_f32 v[232:235], v196, v215, v[232:235]
	v_mfma_f32_16x16x4_f32 v[236:239], v197, v215, v[236:239]
	ds_read_b128 v[198:201], v174 offset:0
	ds_read_b128 v[202:205], v174 offset:64
	ds_read_b128 v[206:209], v174 offset:128
	ds_read_b128 v[210:213], v174 offset:192
	ds_read_b32 v218, v171 offset:1024
	ds_read_b32 v219, v171 offset:1040
	ds_read_b32 v214, v169 offset:2048
	ds_read_b32 v215, v169 offset:3072
	v_mfma_f32_16x16x4_f32 v[224:227], v182, v88, v[224:227]
	v_mfma_f32_16x16x4_f32 v[228:231], v183, v88, v[228:231]
	v_mfma_f32_16x16x4_f32 v[232:235], v184, v88, v[232:235]
	v_mfma_f32_16x16x4_f32 v[236:239], v185, v88, v[236:239]
	v_mfma_f32_16x16x4_f32 v[224:227], v186, v89, v[224:227]
	v_mfma_f32_16x16x4_f32 v[228:231], v187, v89, v[228:231]
	v_mfma_f32_16x16x4_f32 v[232:235], v188, v89, v[232:235]
	v_mfma_f32_16x16x4_f32 v[236:239], v189, v89, v[236:239]
	v_add_u32_e32 v173, 0x880, v173
	v_add_u32_e32 v2, 0x880, v2
	v_add_u32_e32 v3, 0x880, v3
	v_add_u32_e32 v5, 0x880, v5
	ds_read2_b32 v[182:183], v173 offset0:0 offset1:16
	ds_read2_b32 v[184:185], v173 offset0:32 offset1:48
	ds_read2_b32 v[186:187], v2 offset0:0 offset1:16
	ds_read2_b32 v[188:189], v2 offset0:32 offset1:48
	ds_read2_b32 v[190:191], v3 offset0:0 offset1:16
	ds_read2_b32 v[192:193], v3 offset0:32 offset1:48
	ds_read2_b32 v[194:195], v5 offset0:0 offset1:16
	ds_read2_b32 v[196:197], v5 offset0:32 offset1:48
	ds_write2st64_b32 v175, v90, v91 offset0:0 offset1:4
	s_mov_b64 exec, s[14:15]
	ds_add_u32 v179, v241 offset:0
	s_mov_b64 exec, -1
	s_waitcnt lgkmcnt(14)
	v_pk_mul_f32 v[224:225], v[224:225], v[198:199]
	v_pk_mul_f32 v[226:227], v[226:227], v[200:201]
	v_pk_mul_f32 v[228:229], v[228:229], v[202:203]
	v_pk_mul_f32 v[230:231], v[230:231], v[204:205]
	v_mfma_f32_16x16x4_f32 v[36:39], v128, v224, 0
	v_mfma_f32_16x16x4_f32 v[40:43], v129, v225, 0
	v_mfma_f32_16x16x4_f32 v[36:39], v130, v226, v[36:39]
	v_mfma_f32_16x16x4_f32 v[40:43], v131, v227, v[40:43]
	v_pk_mul_f32 v[232:233], v[232:233], v[206:207]
	v_pk_mul_f32 v[234:235], v[234:235], v[208:209]
	v_mfma_f32_16x16x4_f32 v[36:39], v132, v228, v[36:39]
	v_mfma_f32_16x16x4_f32 v[40:43], v133, v229, v[40:43]
	v_mfma_f32_16x16x4_f32 v[36:39], v134, v230, v[36:39]
	v_mfma_f32_16x16x4_f32 v[40:43], v135, v231, v[40:43]
	v_pk_mul_f32 v[236:237], v[236:237], v[210:211]
	v_pk_mul_f32 v[238:239], v[238:239], v[212:213]
	v_mfma_f32_16x16x4_f32 v[36:39], v136, v232, v[36:39]
	v_mfma_f32_16x16x4_f32 v[40:43], v137, v233, v[40:43]
	v_mfma_f32_16x16x4_f32 v[36:39], v138, v234, v[36:39]
	v_mfma_f32_16x16x4_f32 v[40:43], v139, v235, v[40:43]
	v_mfma_f32_16x16x4_f32 v[36:39], v140, v236, v[36:39]
	v_mfma_f32_16x16x4_f32 v[40:43], v141, v237, v[40:43]
	v_mfma_f32_16x16x4_f32 v[36:39], v142, v238, v[36:39]
	v_mfma_f32_16x16x4_f32 v[40:43], v143, v239, v[40:43]
	s_waitcnt lgkmcnt(2)
	v_mfma_f32_16x16x4_f32 v[36:39], v216, v214, v[36:39]
	v_mfma_f32_16x16x4_f32 v[40:43], v217, v215, v[40:43]
	v_mfma_f32_16x16x4_f32 v[224:227], v190, v214, v[224:227]
	v_mfma_f32_16x16x4_f32 v[228:231], v191, v214, v[228:231]
	v_mfma_f32_16x16x4_f32 v[232:235], v192, v214, v[232:235]
	v_mfma_f32_16x16x4_f32 v[236:239], v193, v214, v[236:239]
	ds_read_b128 v[128:131], v168 offset:4352
	ds_read_b128 v[132:135], v168 offset:4416
	ds_read_b128 v[136:139], v168 offset:4480
	ds_read_b128 v[140:143], v168 offset:4544
	ds_read_b32 v216, v171 offset:2304
	ds_read_b32 v217, v171 offset:2320
	v_pk_add_f32 v[84:85], v[36:37], v[40:41]
	v_pk_add_f32 v[82:83], v[38:39], v[42:43]
	s_nop 1
	v_mfma_f32_16x16x4_f32 v[88:91], v218, v84, v[80:83]
	v_mfma_f32_16x16x4_f32 v[88:91], v219, v85, v[88:91]
	v_mfma_f32_16x16x4_f32 v[224:227], v194, v215, v[224:227]
	v_mfma_f32_16x16x4_f32 v[228:231], v195, v215, v[228:231]
	v_mfma_f32_16x16x4_f32 v[232:235], v196, v215, v[232:235]
	v_mfma_f32_16x16x4_f32 v[236:239], v197, v215, v[236:239]
	ds_read_b128 v[198:201], v174 offset:256
	ds_read_b128 v[202:205], v174 offset:320
	ds_read_b128 v[206:209], v174 offset:384
	ds_read_b128 v[210:213], v174 offset:448
	ds_read_b32 v218, v171 offset:2048
	ds_read_b32 v219, v171 offset:2064
	ds_read_b32 v214, v169 offset:4096
	ds_read_b32 v215, v169 offset:5120
	v_mfma_f32_16x16x4_f32 v[224:227], v182, v88, v[224:227]
	v_mfma_f32_16x16x4_f32 v[228:231], v183, v88, v[228:231]
	v_mfma_f32_16x16x4_f32 v[232:235], v184, v88, v[232:235]
	v_mfma_f32_16x16x4_f32 v[236:239], v185, v88, v[236:239]
	v_mfma_f32_16x16x4_f32 v[224:227], v186, v89, v[224:227]
	v_mfma_f32_16x16x4_f32 v[228:231], v187, v89, v[228:231]
	v_mfma_f32_16x16x4_f32 v[232:235], v188, v89, v[232:235]
	v_mfma_f32_16x16x4_f32 v[236:239], v189, v89, v[236:239]
	v_add_u32_e32 v173, 0x880, v173
	v_add_u32_e32 v2, 0x880, v2
	v_add_u32_e32 v3, 0x880, v3
	v_add_u32_e32 v5, 0x880, v5
	ds_read2_b32 v[182:183], v173 offset0:0 offset1:16
	ds_read2_b32 v[184:185], v173 offset0:32 offset1:48
	ds_read2_b32 v[186:187], v2 offset0:0 offset1:16
	ds_read2_b32 v[188:189], v2 offset0:32 offset1:48
	ds_read2_b32 v[190:191], v3 offset0:0 offset1:16
	ds_read2_b32 v[192:193], v3 offset0:32 offset1:48
	ds_read2_b32 v[194:195], v5 offset0:0 offset1:16
	ds_read2_b32 v[196:197], v5 offset0:32 offset1:48
	ds_write2st64_b32 v175, v90, v91 offset0:8 offset1:12
	s_mov_b64 exec, s[14:15]
	ds_add_u32 v179, v241 offset:4
	s_mov_b64 exec, -1
	s_waitcnt lgkmcnt(14)
	v_pk_mul_f32 v[224:225], v[224:225], v[198:199]
	v_pk_mul_f32 v[226:227], v[226:227], v[200:201]
	v_pk_mul_f32 v[228:229], v[228:229], v[202:203]
	v_pk_mul_f32 v[230:231], v[230:231], v[204:205]
	v_mfma_f32_16x16x4_f32 v[36:39], v128, v224, 0
	v_mfma_f32_16x16x4_f32 v[40:43], v129, v225, 0
	v_mfma_f32_16x16x4_f32 v[36:39], v130, v226, v[36:39]
	v_mfma_f32_16x16x4_f32 v[40:43], v131, v227, v[40:43]
	v_pk_mul_f32 v[232:233], v[232:233], v[206:207]
	v_pk_mul_f32 v[234:235], v[234:235], v[208:209]
	v_mfma_f32_16x16x4_f32 v[36:39], v132, v228, v[36:39]
	v_mfma_f32_16x16x4_f32 v[40:43], v133, v229, v[40:43]
	v_mfma_f32_16x16x4_f32 v[36:39], v134, v230, v[36:39]
	v_mfma_f32_16x16x4_f32 v[40:43], v135, v231, v[40:43]
	v_pk_mul_f32 v[236:237], v[236:237], v[210:211]
	v_pk_mul_f32 v[238:239], v[238:239], v[212:213]
	v_mfma_f32_16x16x4_f32 v[36:39], v136, v232, v[36:39]
	v_mfma_f32_16x16x4_f32 v[40:43], v137, v233, v[40:43]
	v_mfma_f32_16x16x4_f32 v[36:39], v138, v234, v[36:39]
	v_mfma_f32_16x16x4_f32 v[40:43], v139, v235, v[40:43]
	v_mfma_f32_16x16x4_f32 v[36:39], v140, v236, v[36:39]
	v_mfma_f32_16x16x4_f32 v[40:43], v141, v237, v[40:43]
	v_mfma_f32_16x16x4_f32 v[36:39], v142, v238, v[36:39]
	v_mfma_f32_16x16x4_f32 v[40:43], v143, v239, v[40:43]
	s_waitcnt lgkmcnt(2)
	v_mfma_f32_16x16x4_f32 v[36:39], v216, v214, v[36:39]
	v_mfma_f32_16x16x4_f32 v[40:43], v217, v215, v[40:43]
	v_mfma_f32_16x16x4_f32 v[224:227], v190, v214, v[224:227]
	v_mfma_f32_16x16x4_f32 v[228:231], v191, v214, v[228:231]
	v_mfma_f32_16x16x4_f32 v[232:235], v192, v214, v[232:235]
	v_mfma_f32_16x16x4_f32 v[236:239], v193, v214, v[236:239]
	ds_read_b128 v[128:131], v168 offset:6528
	ds_read_b128 v[132:135], v168 offset:6592
	ds_read_b128 v[136:139], v168 offset:6656
	ds_read_b128 v[140:143], v168 offset:6720
	ds_read_b32 v216, v171 offset:3328
	ds_read_b32 v217, v171 offset:3344
	v_pk_add_f32 v[84:85], v[36:37], v[40:41]
	v_pk_add_f32 v[82:83], v[38:39], v[42:43]
	s_nop 1
	v_mfma_f32_16x16x4_f32 v[88:91], v218, v84, v[80:83]
	v_mfma_f32_16x16x4_f32 v[88:91], v219, v85, v[88:91]
	v_mfma_f32_16x16x4_f32 v[224:227], v194, v215, v[224:227]
	v_mfma_f32_16x16x4_f32 v[228:231], v195, v215, v[228:231]
	v_mfma_f32_16x16x4_f32 v[232:235], v196, v215, v[232:235]
	v_mfma_f32_16x16x4_f32 v[236:239], v197, v215, v[236:239]
	ds_read_b128 v[198:201], v174 offset:512
	ds_read_b128 v[202:205], v174 offset:576
	ds_read_b128 v[206:209], v174 offset:640
	ds_read_b128 v[210:213], v174 offset:704
	ds_read_b32 v218, v171 offset:3072
	ds_read_b32 v219, v171 offset:3088
	ds_read_b32 v214, v169 offset:6144
	ds_read_b32 v215, v169 offset:7168
	v_mfma_f32_16x16x4_f32 v[224:227], v182, v88, v[224:227]
	v_mfma_f32_16x16x4_f32 v[228:231], v183, v88, v[228:231]
	v_mfma_f32_16x16x4_f32 v[232:235], v184, v88, v[232:235]
	v_mfma_f32_16x16x4_f32 v[236:239], v185, v88, v[236:239]
	v_mfma_f32_16x16x4_f32 v[224:227], v186, v89, v[224:227]
	v_mfma_f32_16x16x4_f32 v[228:231], v187, v89, v[228:231]
	v_mfma_f32_16x16x4_f32 v[232:235], v188, v89, v[232:235]
	v_mfma_f32_16x16x4_f32 v[236:239], v189, v89, v[236:239]
	v_add_u32_e32 v173, 0x880, v173
	v_add_u32_e32 v2, 0x880, v2
	v_add_u32_e32 v3, 0x880, v3
	v_add_u32_e32 v5, 0x880, v5
	ds_read2_b32 v[182:183], v173 offset0:0 offset1:16
	ds_read2_b32 v[184:185], v173 offset0:32 offset1:48
	ds_read2_b32 v[186:187], v2 offset0:0 offset1:16
	ds_read2_b32 v[188:189], v2 offset0:32 offset1:48
	ds_read2_b32 v[190:191], v3 offset0:0 offset1:16
	ds_read2_b32 v[192:193], v3 offset0:32 offset1:48
	ds_read2_b32 v[194:195], v5 offset0:0 offset1:16
	ds_read2_b32 v[196:197], v5 offset0:32 offset1:48
	ds_write2st64_b32 v175, v90, v91 offset0:16 offset1:20
	s_mov_b64 exec, s[14:15]
	ds_add_u32 v179, v241 offset:8
	s_mov_b64 exec, -1
	s_waitcnt lgkmcnt(14)
	v_pk_mul_f32 v[224:225], v[224:225], v[198:199]
	v_pk_mul_f32 v[226:227], v[226:227], v[200:201]
	v_pk_mul_f32 v[228:229], v[228:229], v[202:203]
	v_pk_mul_f32 v[230:231], v[230:231], v[204:205]
	v_mfma_f32_16x16x4_f32 v[36:39], v128, v224, 0
	v_mfma_f32_16x16x4_f32 v[40:43], v129, v225, 0
	v_mfma_f32_16x16x4_f32 v[36:39], v130, v226, v[36:39]
	v_mfma_f32_16x16x4_f32 v[40:43], v131, v227, v[40:43]
	v_pk_mul_f32 v[232:233], v[232:233], v[206:207]
	v_pk_mul_f32 v[234:235], v[234:235], v[208:209]
	v_mfma_f32_16x16x4_f32 v[36:39], v132, v228, v[36:39]
	v_mfma_f32_16x16x4_f32 v[40:43], v133, v229, v[40:43]
	v_mfma_f32_16x16x4_f32 v[36:39], v134, v230, v[36:39]
	v_mfma_f32_16x16x4_f32 v[40:43], v135, v231, v[40:43]
	v_pk_mul_f32 v[236:237], v[236:237], v[210:211]
	v_pk_mul_f32 v[238:239], v[238:239], v[212:213]
	v_mfma_f32_16x16x4_f32 v[36:39], v136, v232, v[36:39]
	v_mfma_f32_16x16x4_f32 v[40:43], v137, v233, v[40:43]
	v_mfma_f32_16x16x4_f32 v[36:39], v138, v234, v[36:39]
	v_mfma_f32_16x16x4_f32 v[40:43], v139, v235, v[40:43]
	v_mfma_f32_16x16x4_f32 v[36:39], v140, v236, v[36:39]
	v_mfma_f32_16x16x4_f32 v[40:43], v141, v237, v[40:43]
	v_mfma_f32_16x16x4_f32 v[36:39], v142, v238, v[36:39]
	v_mfma_f32_16x16x4_f32 v[40:43], v143, v239, v[40:43]
	s_waitcnt lgkmcnt(2)
	v_mfma_f32_16x16x4_f32 v[36:39], v216, v214, v[36:39]
	v_mfma_f32_16x16x4_f32 v[40:43], v217, v215, v[40:43]
	v_mfma_f32_16x16x4_f32 v[224:227], v190, v214, v[224:227]
	v_mfma_f32_16x16x4_f32 v[228:231], v191, v214, v[228:231]
	v_mfma_f32_16x16x4_f32 v[232:235], v192, v214, v[232:235]
	v_mfma_f32_16x16x4_f32 v[236:239], v193, v214, v[236:239]
	ds_read_b128 v[128:131], v168 offset:8704
	ds_read_b128 v[132:135], v168 offset:8768
	ds_read_b128 v[136:139], v168 offset:8832
	ds_read_b128 v[140:143], v168 offset:8896
	ds_read_b32 v216, v171 offset:4352
	ds_read_b32 v217, v171 offset:4368
	v_pk_add_f32 v[84:85], v[36:37], v[40:41]
	v_pk_add_f32 v[82:83], v[38:39], v[42:43]
	s_nop 1
	v_mfma_f32_16x16x4_f32 v[88:91], v218, v84, v[80:83]
	v_mfma_f32_16x16x4_f32 v[88:91], v219, v85, v[88:91]
	v_mfma_f32_16x16x4_f32 v[224:227], v194, v215, v[224:227]
	v_mfma_f32_16x16x4_f32 v[228:231], v195, v215, v[228:231]
	v_mfma_f32_16x16x4_f32 v[232:235], v196, v215, v[232:235]
	v_mfma_f32_16x16x4_f32 v[236:239], v197, v215, v[236:239]
	ds_read_b128 v[198:201], v174 offset:768
	ds_read_b128 v[202:205], v174 offset:832
	ds_read_b128 v[206:209], v174 offset:896
	ds_read_b128 v[210:213], v174 offset:960
	ds_read_b32 v218, v171 offset:4096
	ds_read_b32 v219, v171 offset:4112
	ds_read_b32 v214, v169 offset:8192
	ds_read_b32 v215, v169 offset:9216
	v_mfma_f32_16x16x4_f32 v[224:227], v182, v88, v[224:227]
	v_mfma_f32_16x16x4_f32 v[228:231], v183, v88, v[228:231]
	v_mfma_f32_16x16x4_f32 v[232:235], v184, v88, v[232:235]
	v_mfma_f32_16x16x4_f32 v[236:239], v185, v88, v[236:239]
	v_mfma_f32_16x16x4_f32 v[224:227], v186, v89, v[224:227]
	v_mfma_f32_16x16x4_f32 v[228:231], v187, v89, v[228:231]
	v_mfma_f32_16x16x4_f32 v[232:235], v188, v89, v[232:235]
	v_mfma_f32_16x16x4_f32 v[236:239], v189, v89, v[236:239]
	v_add_u32_e32 v173, 0x880, v173
	v_add_u32_e32 v2, 0x880, v2
	v_add_u32_e32 v3, 0x880, v3
	v_add_u32_e32 v5, 0x880, v5
	ds_read2_b32 v[182:183], v173 offset0:0 offset1:16
	ds_read2_b32 v[184:185], v173 offset0:32 offset1:48
	ds_read2_b32 v[186:187], v2 offset0:0 offset1:16
	ds_read2_b32 v[188:189], v2 offset0:32 offset1:48
	ds_read2_b32 v[190:191], v3 offset0:0 offset1:16
	ds_read2_b32 v[192:193], v3 offset0:32 offset1:48
	ds_read2_b32 v[194:195], v5 offset0:0 offset1:16
	ds_read2_b32 v[196:197], v5 offset0:32 offset1:48
	ds_write2st64_b32 v175, v90, v91 offset0:24 offset1:28
	s_mov_b64 exec, s[14:15]
	ds_add_u32 v179, v241 offset:12
	s_mov_b64 exec, -1
	s_waitcnt lgkmcnt(14)
	v_pk_mul_f32 v[224:225], v[224:225], v[198:199]
	v_pk_mul_f32 v[226:227], v[226:227], v[200:201]
	v_pk_mul_f32 v[228:229], v[228:229], v[202:203]
	v_pk_mul_f32 v[230:231], v[230:231], v[204:205]
	v_mfma_f32_16x16x4_f32 v[36:39], v128, v224, 0
	v_mfma_f32_16x16x4_f32 v[40:43], v129, v225, 0
	v_mfma_f32_16x16x4_f32 v[36:39], v130, v226, v[36:39]
	v_mfma_f32_16x16x4_f32 v[40:43], v131, v227, v[40:43]
	v_pk_mul_f32 v[232:233], v[232:233], v[206:207]
	v_pk_mul_f32 v[234:235], v[234:235], v[208:209]
	v_mfma_f32_16x16x4_f32 v[36:39], v132, v228, v[36:39]
	v_mfma_f32_16x16x4_f32 v[40:43], v133, v229, v[40:43]
	v_mfma_f32_16x16x4_f32 v[36:39], v134, v230, v[36:39]
	v_mfma_f32_16x16x4_f32 v[40:43], v135, v231, v[40:43]
	v_pk_mul_f32 v[236:237], v[236:237], v[210:211]
	v_pk_mul_f32 v[238:239], v[238:239], v[212:213]
	v_mfma_f32_16x16x4_f32 v[36:39], v136, v232, v[36:39]
	v_mfma_f32_16x16x4_f32 v[40:43], v137, v233, v[40:43]
	v_mfma_f32_16x16x4_f32 v[36:39], v138, v234, v[36:39]
	v_mfma_f32_16x16x4_f32 v[40:43], v139, v235, v[40:43]
	v_mfma_f32_16x16x4_f32 v[36:39], v140, v236, v[36:39]
	v_mfma_f32_16x16x4_f32 v[40:43], v141, v237, v[40:43]
	v_mfma_f32_16x16x4_f32 v[36:39], v142, v238, v[36:39]
	v_mfma_f32_16x16x4_f32 v[40:43], v143, v239, v[40:43]
	s_waitcnt lgkmcnt(2)
	v_mfma_f32_16x16x4_f32 v[36:39], v216, v214, v[36:39]
	v_mfma_f32_16x16x4_f32 v[40:43], v217, v215, v[40:43]
	v_mfma_f32_16x16x4_f32 v[224:227], v190, v214, v[224:227]
	v_mfma_f32_16x16x4_f32 v[228:231], v191, v214, v[228:231]
	v_mfma_f32_16x16x4_f32 v[232:235], v192, v214, v[232:235]
	v_mfma_f32_16x16x4_f32 v[236:239], v193, v214, v[236:239]
	ds_read_b128 v[128:131], v168 offset:10880
	ds_read_b128 v[132:135], v168 offset:10944
	ds_read_b128 v[136:139], v168 offset:11008
	ds_read_b128 v[140:143], v168 offset:11072
	ds_read_b32 v216, v171 offset:5376
	ds_read_b32 v217, v171 offset:5392
	v_pk_add_f32 v[84:85], v[36:37], v[40:41]
	v_pk_add_f32 v[82:83], v[38:39], v[42:43]
	s_nop 1
	v_mfma_f32_16x16x4_f32 v[88:91], v218, v84, v[80:83]
	v_mfma_f32_16x16x4_f32 v[88:91], v219, v85, v[88:91]
	v_mfma_f32_16x16x4_f32 v[224:227], v194, v215, v[224:227]
	v_mfma_f32_16x16x4_f32 v[228:231], v195, v215, v[228:231]
	v_mfma_f32_16x16x4_f32 v[232:235], v196, v215, v[232:235]
	v_mfma_f32_16x16x4_f32 v[236:239], v197, v215, v[236:239]
	ds_read_b128 v[198:201], v174 offset:1024
	ds_read_b128 v[202:205], v174 offset:1088
	ds_read_b128 v[206:209], v174 offset:1152
	ds_read_b128 v[210:213], v174 offset:1216
	ds_read_b32 v218, v171 offset:5120
	ds_read_b32 v219, v171 offset:5136
	ds_read_b32 v214, v169 offset:10240
	ds_read_b32 v215, v169 offset:11264
	v_mfma_f32_16x16x4_f32 v[224:227], v182, v88, v[224:227]
	v_mfma_f32_16x16x4_f32 v[228:231], v183, v88, v[228:231]
	v_mfma_f32_16x16x4_f32 v[232:235], v184, v88, v[232:235]
	v_mfma_f32_16x16x4_f32 v[236:239], v185, v88, v[236:239]
	v_mfma_f32_16x16x4_f32 v[224:227], v186, v89, v[224:227]
	v_mfma_f32_16x16x4_f32 v[228:231], v187, v89, v[228:231]
	v_mfma_f32_16x16x4_f32 v[232:235], v188, v89, v[232:235]
	v_mfma_f32_16x16x4_f32 v[236:239], v189, v89, v[236:239]
	v_add_u32_e32 v173, 0x880, v173
	v_add_u32_e32 v2, 0x880, v2
	v_add_u32_e32 v3, 0x880, v3
	v_add_u32_e32 v5, 0x880, v5
	ds_read2_b32 v[182:183], v173 offset0:0 offset1:16
	ds_read2_b32 v[184:185], v173 offset0:32 offset1:48
	ds_read2_b32 v[186:187], v2 offset0:0 offset1:16
	ds_read2_b32 v[188:189], v2 offset0:32 offset1:48
	ds_read2_b32 v[190:191], v3 offset0:0 offset1:16
	ds_read2_b32 v[192:193], v3 offset0:32 offset1:48
	ds_read2_b32 v[194:195], v5 offset0:0 offset1:16
	ds_read2_b32 v[196:197], v5 offset0:32 offset1:48
	ds_write2st64_b32 v175, v90, v91 offset0:32 offset1:36
	s_mov_b64 exec, s[14:15]
	ds_add_u32 v179, v241 offset:16
	s_mov_b64 exec, -1
	s_waitcnt lgkmcnt(14)
	v_pk_mul_f32 v[224:225], v[224:225], v[198:199]
	v_pk_mul_f32 v[226:227], v[226:227], v[200:201]
	v_pk_mul_f32 v[228:229], v[228:229], v[202:203]
	v_pk_mul_f32 v[230:231], v[230:231], v[204:205]
	v_mfma_f32_16x16x4_f32 v[36:39], v128, v224, 0
	v_mfma_f32_16x16x4_f32 v[40:43], v129, v225, 0
	v_mfma_f32_16x16x4_f32 v[36:39], v130, v226, v[36:39]
	v_mfma_f32_16x16x4_f32 v[40:43], v131, v227, v[40:43]
	v_pk_mul_f32 v[232:233], v[232:233], v[206:207]
	v_pk_mul_f32 v[234:235], v[234:235], v[208:209]
	v_mfma_f32_16x16x4_f32 v[36:39], v132, v228, v[36:39]
	v_mfma_f32_16x16x4_f32 v[40:43], v133, v229, v[40:43]
	v_mfma_f32_16x16x4_f32 v[36:39], v134, v230, v[36:39]
	v_mfma_f32_16x16x4_f32 v[40:43], v135, v231, v[40:43]
	v_pk_mul_f32 v[236:237], v[236:237], v[210:211]
	v_pk_mul_f32 v[238:239], v[238:239], v[212:213]
	v_mfma_f32_16x16x4_f32 v[36:39], v136, v232, v[36:39]
	v_mfma_f32_16x16x4_f32 v[40:43], v137, v233, v[40:43]
	v_mfma_f32_16x16x4_f32 v[36:39], v138, v234, v[36:39]
	v_mfma_f32_16x16x4_f32 v[40:43], v139, v235, v[40:43]
	v_mfma_f32_16x16x4_f32 v[36:39], v140, v236, v[36:39]
	v_mfma_f32_16x16x4_f32 v[40:43], v141, v237, v[40:43]
	v_mfma_f32_16x16x4_f32 v[36:39], v142, v238, v[36:39]
	v_mfma_f32_16x16x4_f32 v[40:43], v143, v239, v[40:43]
	s_waitcnt lgkmcnt(2)
	v_mfma_f32_16x16x4_f32 v[36:39], v216, v214, v[36:39]
	v_mfma_f32_16x16x4_f32 v[40:43], v217, v215, v[40:43]
	v_mfma_f32_16x16x4_f32 v[224:227], v190, v214, v[224:227]
	v_mfma_f32_16x16x4_f32 v[228:231], v191, v214, v[228:231]
	v_mfma_f32_16x16x4_f32 v[232:235], v192, v214, v[232:235]
	v_mfma_f32_16x16x4_f32 v[236:239], v193, v214, v[236:239]
	ds_read_b128 v[128:131], v168 offset:13056
	ds_read_b128 v[132:135], v168 offset:13120
	ds_read_b128 v[136:139], v168 offset:13184
	ds_read_b128 v[140:143], v168 offset:13248
	ds_read_b32 v216, v171 offset:6400
	ds_read_b32 v217, v171 offset:6416
	v_pk_add_f32 v[84:85], v[36:37], v[40:41]
	v_pk_add_f32 v[82:83], v[38:39], v[42:43]
	s_nop 1
	v_mfma_f32_16x16x4_f32 v[88:91], v218, v84, v[80:83]
	v_mfma_f32_16x16x4_f32 v[88:91], v219, v85, v[88:91]
	v_mfma_f32_16x16x4_f32 v[224:227], v194, v215, v[224:227]
	v_mfma_f32_16x16x4_f32 v[228:231], v195, v215, v[228:231]
	v_mfma_f32_16x16x4_f32 v[232:235], v196, v215, v[232:235]
	v_mfma_f32_16x16x4_f32 v[236:239], v197, v215, v[236:239]
	ds_read_b128 v[198:201], v174 offset:1280
	ds_read_b128 v[202:205], v174 offset:1344
	ds_read_b128 v[206:209], v174 offset:1408
	ds_read_b128 v[210:213], v174 offset:1472
	ds_read_b32 v218, v171 offset:6144
	ds_read_b32 v219, v171 offset:6160
	ds_read_b32 v214, v169 offset:12288
	ds_read_b32 v215, v169 offset:13312
	v_mfma_f32_16x16x4_f32 v[224:227], v182, v88, v[224:227]
	v_mfma_f32_16x16x4_f32 v[228:231], v183, v88, v[228:231]
	v_mfma_f32_16x16x4_f32 v[232:235], v184, v88, v[232:235]
	v_mfma_f32_16x16x4_f32 v[236:239], v185, v88, v[236:239]
	v_mfma_f32_16x16x4_f32 v[224:227], v186, v89, v[224:227]
	v_mfma_f32_16x16x4_f32 v[228:231], v187, v89, v[228:231]
	v_mfma_f32_16x16x4_f32 v[232:235], v188, v89, v[232:235]
	v_mfma_f32_16x16x4_f32 v[236:239], v189, v89, v[236:239]
	v_add_u32_e32 v173, 0x880, v173
	v_add_u32_e32 v2, 0x880, v2
	v_add_u32_e32 v3, 0x880, v3
	v_add_u32_e32 v5, 0x880, v5
	ds_read2_b32 v[182:183], v173 offset0:0 offset1:16
	ds_read2_b32 v[184:185], v173 offset0:32 offset1:48
	ds_read2_b32 v[186:187], v2 offset0:0 offset1:16
	ds_read2_b32 v[188:189], v2 offset0:32 offset1:48
	ds_read2_b32 v[190:191], v3 offset0:0 offset1:16
	ds_read2_b32 v[192:193], v3 offset0:32 offset1:48
	ds_read2_b32 v[194:195], v5 offset0:0 offset1:16
	ds_read2_b32 v[196:197], v5 offset0:32 offset1:48
	ds_write2st64_b32 v175, v90, v91 offset0:40 offset1:44
	s_mov_b64 exec, s[14:15]
	ds_add_u32 v179, v241 offset:20
	s_mov_b64 exec, -1
	s_waitcnt lgkmcnt(14)
	v_pk_mul_f32 v[224:225], v[224:225], v[198:199]
	v_pk_mul_f32 v[226:227], v[226:227], v[200:201]
	v_pk_mul_f32 v[228:229], v[228:229], v[202:203]
	v_pk_mul_f32 v[230:231], v[230:231], v[204:205]
	v_mfma_f32_16x16x4_f32 v[36:39], v128, v224, 0
	v_mfma_f32_16x16x4_f32 v[40:43], v129, v225, 0
	v_mfma_f32_16x16x4_f32 v[36:39], v130, v226, v[36:39]
	v_mfma_f32_16x16x4_f32 v[40:43], v131, v227, v[40:43]
	v_pk_mul_f32 v[232:233], v[232:233], v[206:207]
	v_pk_mul_f32 v[234:235], v[234:235], v[208:209]
	v_mfma_f32_16x16x4_f32 v[36:39], v132, v228, v[36:39]
	v_mfma_f32_16x16x4_f32 v[40:43], v133, v229, v[40:43]
	v_mfma_f32_16x16x4_f32 v[36:39], v134, v230, v[36:39]
	v_mfma_f32_16x16x4_f32 v[40:43], v135, v231, v[40:43]
	v_pk_mul_f32 v[236:237], v[236:237], v[210:211]
	v_pk_mul_f32 v[238:239], v[238:239], v[212:213]
	v_mfma_f32_16x16x4_f32 v[36:39], v136, v232, v[36:39]
	v_mfma_f32_16x16x4_f32 v[40:43], v137, v233, v[40:43]
	v_mfma_f32_16x16x4_f32 v[36:39], v138, v234, v[36:39]
	v_mfma_f32_16x16x4_f32 v[40:43], v139, v235, v[40:43]
	v_mfma_f32_16x16x4_f32 v[36:39], v140, v236, v[36:39]
	v_mfma_f32_16x16x4_f32 v[40:43], v141, v237, v[40:43]
	v_mfma_f32_16x16x4_f32 v[36:39], v142, v238, v[36:39]
	v_mfma_f32_16x16x4_f32 v[40:43], v143, v239, v[40:43]
	s_waitcnt lgkmcnt(2)
	v_mfma_f32_16x16x4_f32 v[36:39], v216, v214, v[36:39]
	v_mfma_f32_16x16x4_f32 v[40:43], v217, v215, v[40:43]
	v_mfma_f32_16x16x4_f32 v[224:227], v190, v214, v[224:227]
	v_mfma_f32_16x16x4_f32 v[228:231], v191, v214, v[228:231]
	v_mfma_f32_16x16x4_f32 v[232:235], v192, v214, v[232:235]
	v_mfma_f32_16x16x4_f32 v[236:239], v193, v214, v[236:239]
	ds_read_b128 v[128:131], v168 offset:15232
	ds_read_b128 v[132:135], v168 offset:15296
	ds_read_b128 v[136:139], v168 offset:15360
	ds_read_b128 v[140:143], v168 offset:15424
	ds_read_b32 v216, v171 offset:7424
	ds_read_b32 v217, v171 offset:7440
	v_pk_add_f32 v[84:85], v[36:37], v[40:41]
	v_pk_add_f32 v[82:83], v[38:39], v[42:43]
	s_nop 1
	v_mfma_f32_16x16x4_f32 v[88:91], v218, v84, v[80:83]
	v_mfma_f32_16x16x4_f32 v[88:91], v219, v85, v[88:91]
	v_mfma_f32_16x16x4_f32 v[224:227], v194, v215, v[224:227]
	v_mfma_f32_16x16x4_f32 v[228:231], v195, v215, v[228:231]
	v_mfma_f32_16x16x4_f32 v[232:235], v196, v215, v[232:235]
	v_mfma_f32_16x16x4_f32 v[236:239], v197, v215, v[236:239]
	ds_read_b128 v[198:201], v174 offset:1536
	ds_read_b128 v[202:205], v174 offset:1600
	ds_read_b128 v[206:209], v174 offset:1664
	ds_read_b128 v[210:213], v174 offset:1728
	ds_read_b32 v218, v171 offset:7168
	ds_read_b32 v219, v171 offset:7184
	ds_read_b32 v214, v169 offset:14336
	ds_read_b32 v215, v169 offset:15360
	v_mfma_f32_16x16x4_f32 v[224:227], v182, v88, v[224:227]
	v_mfma_f32_16x16x4_f32 v[228:231], v183, v88, v[228:231]
	v_mfma_f32_16x16x4_f32 v[232:235], v184, v88, v[232:235]
	v_mfma_f32_16x16x4_f32 v[236:239], v185, v88, v[236:239]
	v_mfma_f32_16x16x4_f32 v[224:227], v186, v89, v[224:227]
	v_mfma_f32_16x16x4_f32 v[228:231], v187, v89, v[228:231]
	v_mfma_f32_16x16x4_f32 v[232:235], v188, v89, v[232:235]
	v_mfma_f32_16x16x4_f32 v[236:239], v189, v89, v[236:239]
	v_add_u32_e32 v173, 0x880, v173
	v_add_u32_e32 v2, 0x880, v2
	v_add_u32_e32 v3, 0x880, v3
	v_add_u32_e32 v5, 0x880, v5
	ds_read2_b32 v[182:183], v173 offset0:0 offset1:16
	ds_read2_b32 v[184:185], v173 offset0:32 offset1:48
	ds_read2_b32 v[186:187], v2 offset0:0 offset1:16
	ds_read2_b32 v[188:189], v2 offset0:32 offset1:48
	ds_read2_b32 v[190:191], v3 offset0:0 offset1:16
	ds_read2_b32 v[192:193], v3 offset0:32 offset1:48
	ds_read2_b32 v[194:195], v5 offset0:0 offset1:16
	ds_read2_b32 v[196:197], v5 offset0:32 offset1:48
	ds_write2st64_b32 v175, v90, v91 offset0:48 offset1:52
	s_mov_b64 exec, s[14:15]
	ds_add_u32 v179, v241 offset:24
	s_mov_b64 exec, -1
	s_waitcnt lgkmcnt(14)
	v_pk_mul_f32 v[224:225], v[224:225], v[198:199]
	v_pk_mul_f32 v[226:227], v[226:227], v[200:201]
	v_pk_mul_f32 v[228:229], v[228:229], v[202:203]
	v_pk_mul_f32 v[230:231], v[230:231], v[204:205]
	v_mfma_f32_16x16x4_f32 v[36:39], v128, v224, 0
	v_mfma_f32_16x16x4_f32 v[40:43], v129, v225, 0
	v_mfma_f32_16x16x4_f32 v[36:39], v130, v226, v[36:39]
	v_mfma_f32_16x16x4_f32 v[40:43], v131, v227, v[40:43]
	v_pk_mul_f32 v[232:233], v[232:233], v[206:207]
	v_pk_mul_f32 v[234:235], v[234:235], v[208:209]
	v_mfma_f32_16x16x4_f32 v[36:39], v132, v228, v[36:39]
	v_mfma_f32_16x16x4_f32 v[40:43], v133, v229, v[40:43]
	v_mfma_f32_16x16x4_f32 v[36:39], v134, v230, v[36:39]
	v_mfma_f32_16x16x4_f32 v[40:43], v135, v231, v[40:43]
	v_pk_mul_f32 v[236:237], v[236:237], v[210:211]
	v_pk_mul_f32 v[238:239], v[238:239], v[212:213]
	v_mfma_f32_16x16x4_f32 v[36:39], v136, v232, v[36:39]
	v_mfma_f32_16x16x4_f32 v[40:43], v137, v233, v[40:43]
	v_mfma_f32_16x16x4_f32 v[36:39], v138, v234, v[36:39]
	v_mfma_f32_16x16x4_f32 v[40:43], v139, v235, v[40:43]
	v_mfma_f32_16x16x4_f32 v[36:39], v140, v236, v[36:39]
	v_mfma_f32_16x16x4_f32 v[40:43], v141, v237, v[40:43]
	v_mfma_f32_16x16x4_f32 v[36:39], v142, v238, v[36:39]
	v_mfma_f32_16x16x4_f32 v[40:43], v143, v239, v[40:43]
	s_waitcnt lgkmcnt(2)
	v_mfma_f32_16x16x4_f32 v[36:39], v216, v214, v[36:39]
	v_mfma_f32_16x16x4_f32 v[40:43], v217, v215, v[40:43]
	v_mfma_f32_16x16x4_f32 v[224:227], v190, v214, v[224:227]
	v_mfma_f32_16x16x4_f32 v[228:231], v191, v214, v[228:231]
	v_mfma_f32_16x16x4_f32 v[232:235], v192, v214, v[232:235]
	v_mfma_f32_16x16x4_f32 v[236:239], v193, v214, v[236:239]
	ds_read_b128 v[128:131], v168 offset:17408
	ds_read_b128 v[132:135], v168 offset:17472
	ds_read_b128 v[136:139], v168 offset:17536
	ds_read_b128 v[140:143], v168 offset:17600
	ds_read_b32 v216, v171 offset:8448
	ds_read_b32 v217, v171 offset:8464
	v_pk_add_f32 v[84:85], v[36:37], v[40:41]
	v_pk_add_f32 v[82:83], v[38:39], v[42:43]
	s_nop 1
	v_mfma_f32_16x16x4_f32 v[88:91], v218, v84, v[80:83]
	v_mfma_f32_16x16x4_f32 v[88:91], v219, v85, v[88:91]
	v_mfma_f32_16x16x4_f32 v[224:227], v194, v215, v[224:227]
	v_mfma_f32_16x16x4_f32 v[228:231], v195, v215, v[228:231]
	v_mfma_f32_16x16x4_f32 v[232:235], v196, v215, v[232:235]
	v_mfma_f32_16x16x4_f32 v[236:239], v197, v215, v[236:239]
	ds_read_b128 v[198:201], v174 offset:1792
	ds_read_b128 v[202:205], v174 offset:1856
	ds_read_b128 v[206:209], v174 offset:1920
	ds_read_b128 v[210:213], v174 offset:1984
	ds_read_b32 v218, v171 offset:8192
	ds_read_b32 v219, v171 offset:8208
	ds_read_b32 v214, v169 offset:16384
	ds_read_b32 v215, v169 offset:17408
	v_mfma_f32_16x16x4_f32 v[224:227], v182, v88, v[224:227]
	v_mfma_f32_16x16x4_f32 v[228:231], v183, v88, v[228:231]
	v_mfma_f32_16x16x4_f32 v[232:235], v184, v88, v[232:235]
	v_mfma_f32_16x16x4_f32 v[236:239], v185, v88, v[236:239]
	v_mfma_f32_16x16x4_f32 v[224:227], v186, v89, v[224:227]
	v_mfma_f32_16x16x4_f32 v[228:231], v187, v89, v[228:231]
	v_mfma_f32_16x16x4_f32 v[232:235], v188, v89, v[232:235]
	v_mfma_f32_16x16x4_f32 v[236:239], v189, v89, v[236:239]
	v_add_u32_e32 v173, 0x880, v173
	v_add_u32_e32 v2, 0x880, v2
	v_add_u32_e32 v3, 0x880, v3
	v_add_u32_e32 v5, 0x880, v5
	ds_read2_b32 v[182:183], v173 offset0:0 offset1:16
	ds_read2_b32 v[184:185], v173 offset0:32 offset1:48
	ds_read2_b32 v[186:187], v2 offset0:0 offset1:16
	ds_read2_b32 v[188:189], v2 offset0:32 offset1:48
	ds_read2_b32 v[190:191], v3 offset0:0 offset1:16
	ds_read2_b32 v[192:193], v3 offset0:32 offset1:48
	ds_read2_b32 v[194:195], v5 offset0:0 offset1:16
	ds_read2_b32 v[196:197], v5 offset0:32 offset1:48
	ds_write2st64_b32 v175, v90, v91 offset0:56 offset1:60
	s_mov_b64 exec, s[14:15]
	ds_add_u32 v179, v241 offset:28
	s_mov_b64 exec, -1
	s_waitcnt lgkmcnt(0)
	s_nop 7
	v_pk_mul_f32 v[224:225], v[224:225], v[198:199]
	v_pk_mul_f32 v[226:227], v[226:227], v[200:201]
	v_pk_mul_f32 v[228:229], v[228:229], v[202:203]
	v_pk_mul_f32 v[230:231], v[230:231], v[204:205]
	v_pk_mul_f32 v[232:233], v[232:233], v[206:207]
	v_pk_mul_f32 v[234:235], v[234:235], v[208:209]
	v_pk_mul_f32 v[236:237], v[236:237], v[210:211]
	v_pk_mul_f32 v[238:239], v[238:239], v[212:213]
	s_branch .Lrw_done

.Lrw_go_0:
	s_waitcnt vmcnt(0)
	ds_read2st64_b32 v[150:151], v146 offset0:0 offset1:4
	ds_read2st64_b32 v[152:153], v147 offset0:0 offset1:4
	ds_read2_b32 v[154:155], v148 offset0:0 offset1:4
	v_lshlrev_b32_e32 v128, 16, v128
	v_lshlrev_b32_e32 v129, 16, v129
	s_waitcnt lgkmcnt(0)
	v_pk_mov_b32 v[156:157], v[150:151], v[150:151] op_sel:[0,1]
	s_nop 1
	v_permlane32_swap_b32_e32 v156, v157
	v_add_f32_e32 v156, v156, v157
	v_pk_mul_f32 v[162:163], v[128:129], s[8:9] op_sel_hi:[1,0]
	v_exp_f32_e32 v162, v162
	v_add_f32_dpp v156, v156, v156 quad_perm:[1,0,3,2] row_mask:0xf bank_mask:0xf bound_ctrl:1
	v_exp_f32_e32 v163, v163
	s_nop 0
	v_add_f32_dpp v156, v156, v156 quad_perm:[2,3,0,1] row_mask:0xf bank_mask:0xf bound_ctrl:1
	s_nop 0
	s_nop 0
	v_add_f32_dpp v156, v156, v156 row_half_mirror row_mask:0xf bank_mask:0xf bound_ctrl:1
	s_nop 0
	s_nop 0
	v_add_f32_dpp v156, v156, v156 row_mirror row_mask:0xf bank_mask:0xf bound_ctrl:1
	s_nop 0
	s_nop 0
	v_add_f32_dpp v156, v156, v156 row_bcast:15 row_mask:0xa bank_mask:0xf
	s_nop 0
	v_readlane_b32 s4, v156, 31
	v_readlane_b32 s5, v156, 63
	s_nop 1
	v_pk_fma_f32 v[150:151], s[4:5], v[124:125], v[150:151] op_sel:[0,1,0] op_sel_hi:[1,1,1]
	v_pk_mul_f32 v[158:159], v[150:151], v[150:151]
	s_nop 1
	v_permlane32_swap_b32_e32 v158, v159
	v_add_f32_e32 v158, v158, v159
	v_pk_add_f32 v[162:163], v[162:163], 1.0 op_sel_hi:[1,0]
	v_rcp_f32_e32 v162, v162
	v_add_f32_dpp v158, v158, v158 quad_perm:[1,0,3,2] row_mask:0xf bank_mask:0xf bound_ctrl:1
	v_rcp_f32_e32 v163, v163
	s_nop 0
	v_add_f32_dpp v158, v158, v158 quad_perm:[2,3,0,1] row_mask:0xf bank_mask:0xf bound_ctrl:1
	s_nop 0
	s_nop 0
	v_add_f32_dpp v158, v158, v158 row_half_mirror row_mask:0xf bank_mask:0xf bound_ctrl:1
	s_nop 0
	s_nop 0
	v_add_f32_dpp v158, v158, v158 row_mirror row_mask:0xf bank_mask:0xf bound_ctrl:1
	s_nop 0
	s_nop 0
	v_add_f32_dpp v158, v158, v158 row_bcast:15 row_mask:0xa bank_mask:0xf
	s_nop 0
	v_readlane_b32 s6, v158, 31
	v_readlane_b32 s7, v158, 63
	s_nop 1
	v_pk_fma_f32 v[160:161], s[6:7], v[126:127], v[126:127] op_sel:[0,0,1] op_sel_hi:[1,0,1]
	v_rsq_f32_e32 v160, v160
	v_rsq_f32_e32 v161, v161
	s_nop 0
	v_pk_mul_f32 v[164:165], v[150:151], v[160:161]
	v_pk_fma_f32 v[164:165], v[144:145], v[164:165], v[144:145] op_sel:[0,0,1] op_sel_hi:[0,1,1]
	v_pk_fma_f32 v[164:165], v[154:155], v[152:153], v[164:165]
	v_pk_mul_f32 v[164:165], v[164:165], v[128:129]
	v_pk_mul_f32 v[164:165], v[162:163], v[164:165]
	v_bfe_u32 v156, v164, 16, 1
	v_add3_u32 v164, v164, v156, s97
	v_bfe_u32 v157, v165, 16, 1
	v_add3_u32 v165, v165, v157, s97
	global_store_short_d16_hi v124, v164, s[12:13]
	s_add_u32 s12, s12, 0x1000
	s_addc_u32 s13, s13, 0
	global_store_short_d16_hi v124, v165, s[12:13]
	s_add_u32 s12, s12, 0x1000
	s_addc_u32 s13, s13, 0
	s_cmp_lg_u32 s40, 31
	s_cbranch_scc0 .Lrw_nopf
	s_add_i32 s3, s17, 64
	s_add_u32 s0, s80, s3
	s_addc_u32 s1, s81, 0
	v_ashrrev_i32_e32 v27, 31, v26
	v_lshl_add_u64 v[4:5], s[0:1], 0, v[26:27]
	v_mad_u64_u32 v[2:3], s[0:1], v4, s83, 0
	v_mad_i32_i24 v3, v5, s83, v3
	v_add_u32_e32 v33, s3, v26
	v_mov_b32_e32 v95, v94
	v_lshl_add_u64 v[2:3], s[46:47], 0, v[2:3]
	v_cmp_lt_i32_e32 vcc, 0, v33
	v_mov_b32_e32 v106, 0
	v_lshl_add_u64 v[2:3], v[28:29], 1, v[2:3]
	v_mov_b64_e32 v[34:35], v[94:95]
	s_and_saveexec_b64 s[0:1], vcc
	s_cbranch_execz .Lrw_pf585
	global_load_short_d16_hi v106, v[2:3], off offset:-3072
	global_load_short_d16_hi v35, v[2:3], off offset:-2048
	global_load_short_d16_hi v34, v[2:3], off offset:-1024

.Lrw_go_7:
	ds_read2st64_b32 v[150:151], v146 offset0:56 offset1:60
	ds_read2st64_b32 v[152:153], v147 offset0:56 offset1:60
	ds_read2_b32 v[154:155], v148 offset0:56 offset1:60
	v_lshlrev_b32_e32 v142, 16, v142
	v_lshlrev_b32_e32 v143, 16, v143
	s_waitcnt lgkmcnt(0)
	v_pk_mov_b32 v[156:157], v[150:151], v[150:151] op_sel:[0,1]
	s_nop 1
	v_permlane32_swap_b32_e32 v156, v157
	v_add_f32_e32 v156, v156, v157
	v_pk_mul_f32 v[162:163], v[142:143], s[8:9] op_sel_hi:[1,0]
	v_exp_f32_e32 v162, v162
	v_add_f32_dpp v156, v156, v156 quad_perm:[1,0,3,2] row_mask:0xf bank_mask:0xf bound_ctrl:1
	v_exp_f32_e32 v163, v163
	s_nop 0
	v_add_f32_dpp v156, v156, v156 quad_perm:[2,3,0,1] row_mask:0xf bank_mask:0xf bound_ctrl:1
	s_nop 0
	s_nop 0
	v_add_f32_dpp v156, v156, v156 row_half_mirror row_mask:0xf bank_mask:0xf bound_ctrl:1
	s_nop 0
	s_nop 0
	v_add_f32_dpp v156, v156, v156 row_mirror row_mask:0xf bank_mask:0xf bound_ctrl:1
	s_nop 0
	s_nop 0
	v_add_f32_dpp v156, v156, v156 row_bcast:15 row_mask:0xa bank_mask:0xf
	s_nop 0
	v_readlane_b32 s4, v156, 31
	v_readlane_b32 s5, v156, 63
	s_nop 1
	v_pk_fma_f32 v[150:151], s[4:5], v[124:125], v[150:151] op_sel:[0,1,0] op_sel_hi:[1,1,1]
	v_pk_mul_f32 v[158:159], v[150:151], v[150:151]
	s_nop 1
	v_permlane32_swap_b32_e32 v158, v159
	v_add_f32_e32 v158, v158, v159
	v_pk_add_f32 v[162:163], v[162:163], 1.0 op_sel_hi:[1,0]
	v_rcp_f32_e32 v162, v162
	v_add_f32_dpp v158, v158, v158 quad_perm:[1,0,3,2] row_mask:0xf bank_mask:0xf bound_ctrl:1
	v_rcp_f32_e32 v163, v163
	s_nop 0
	v_add_f32_dpp v158, v158, v158 quad_perm:[2,3,0,1] row_mask:0xf bank_mask:0xf bound_ctrl:1
	s_nop 0
	s_nop 0
	v_add_f32_dpp v158, v158, v158 row_half_mirror row_mask:0xf bank_mask:0xf bound_ctrl:1
	s_nop 0
	s_nop 0
	v_add_f32_dpp v158, v158, v158 row_mirror row_mask:0xf bank_mask:0xf bound_ctrl:1
	s_nop 0
	s_nop 0
	v_add_f32_dpp v158, v158, v158 row_bcast:15 row_mask:0xa bank_mask:0xf
	s_nop 0
	v_readlane_b32 s6, v158, 31
	v_readlane_b32 s7, v158, 63
	s_nop 1
	v_pk_fma_f32 v[160:161], s[6:7], v[126:127], v[126:127] op_sel:[0,0,1] op_sel_hi:[1,0,1]
	v_rsq_f32_e32 v160, v160
	v_rsq_f32_e32 v161, v161
	s_nop 0
	v_pk_mul_f32 v[164:165], v[150:151], v[160:161]
	v_pk_fma_f32 v[164:165], v[144:145], v[164:165], v[144:145] op_sel:[0,0,1] op_sel_hi:[0,1,1]
	v_pk_fma_f32 v[164:165], v[154:155], v[152:153], v[164:165]
	v_pk_mul_f32 v[164:165], v[164:165], v[142:143]
	v_pk_mul_f32 v[164:165], v[162:163], v[164:165]
	v_bfe_u32 v156, v164, 16, 1
	v_add3_u32 v164, v164, v156, s97
	v_bfe_u32 v157, v165, 16, 1
	v_add3_u32 v165, v165, v157, s97
	global_store_short_d16_hi v124, v164, s[12:13]
	s_add_u32 s12, s12, 0x1000
	s_addc_u32 s13, s13, 0
	global_store_short_d16_hi v124, v165, s[12:13]
	s_add_u32 s12, s12, 0x1000
	s_addc_u32 s13, s13, 0
	s_waitcnt vmcnt(14)
	s_branch .Lrw_noladder
.Lrw_done:
	s_waitcnt vmcnt(0)
.Lrw_noladder:
	s_add_i32 s40, s40, 1
	s_barrier
	s_cmp_eq_u32 s40, 32
	s_cbranch_scc0 .LBB0_564
	s_branch .LBB0_532
